# same instructions as previous; up-GEMM tile loop header at 32 mod 64 and down-GEMM tile loop header at 56 mod 64
# baseline (speedup 1.0000x reference)
; #define PG8_BAR __builtin_amdgcn_s_barrier()
; template <class Epi, class Sched, bool ALIGN_EPI = false, bool SP2 = false>
; __device__ __forceinline__ void gemm_phase(PG8_LAS unsigned char* lds, const Gemm g, const Sched& S, const Epi& E) {
;     ...
;         if (!has_next) break;
; #pragma unroll
;         for (int a = 0; a < 2; ++a)
; #pragma unroll
;             for (int b = 0; b < 2; ++b)
; #pragma unroll
;                 for (int m = 0; m < 4; ++m)
; #pragma unroll
;                     for (int n = 0; n < 2; ++n) acc[a][b][m][n] = (f32x4){0.f, 0.f, 0.f, 0.f};
;         cur = nxt; cA = nA; cB = nB; ++ui;
;         if constexpr (ALIGN_EPI) { if (wr == 1) PG8_BAR; }
.LBB0_741:
	s_andn2_b64 vcc, exec, s[4:5]
	s_mov_b32 s66, s40
	s_mov_b32 s34, s42
	s_mov_b64 s[10:11], s[46:47]
	s_mov_b64 s[8:9], s[44:45]
	s_cbranch_vccz .LBB0_763
	s_nop 0
	s_nop 0
	s_nop 0
	s_nop 0

; __device__ __forceinline__ void unpack8(const u32x4 w, float (&f)[8]) { f[0] = bf_lo(w.x); f[1] = bf_hi(w.x); f[2] = bf_lo(w.y); f[3] = bf_hi(w.y); f[4] = bf_lo(w.z); f[5] = bf_hi(w.z); f[6] = bf_lo(w.w); f[7] = bf_hi(w.w); }
; __device__ __forceinline__ u32x4 pack8(const float (&f)[8]) { u32x4 o; o.x = pk2(f[0], f[1]); o.y = pk2(f[2], f[3]); o.z = pk2(f[4], f[5]); o.w = pk2(f[6], f[7]); return o; }
; __device__ __forceinline__ float siluf_(float x) { return x * __builtin_amdgcn_rcpf(1.0f + __builtin_amdgcn_exp2f(x * -1.4426950408889634f)); }
; __device__ __forceinline__ void phase_fixup(const Args& a) {
;     const bf16_t* halo = (const bf16_t*)(a.ws + WS_HALO); bf16_t* act = (bf16_t*)(a.ws + WS_ACT);
;     const float* fw = a.in[13]; const float* fb = a.in[14];
;     const int total = 512 * 2 * 352;
;     for (int it = blockIdx.x * NT + threadIdx.x; it < total; it += gridDim.x * NT) {
;         const int p = it % 352, rs = it / 352, rho = rs & 1, seg = rs >> 1, j0 = p * 8; const bool first = (seg & 31) == 0; const size_t t = (size_t)seg * 64 + rho;
;         float o[2][8];
; #pragma unroll
;         for (int bj = 0; bj < 2; ++bj) { const int col = bj * DFF + j0;
;             float cur[8], m1[8], m2[8];
;             unpack8(*(const u32x4*)(halo + ((size_t)(seg * 4 + rho) * 2 + bj) * DFF + j0), cur);
; #pragma unroll
;             for (int e = 0; e < 8; ++e) { m1[e] = 0.f; m2[e] = 0.f; }
;             if (rho == 1) { unpack8(*(const u32x4*)(halo + ((size_t)(seg * 4 + 0) * 2 + bj) * DFF + j0), m1);
;                 if (!first) unpack8(*(const u32x4*)(halo + ((size_t)((seg - 1) * 4 + 3) * 2 + bj) * DFF + j0), m2); }
;             else if (!first) { unpack8(*(const u32x4*)(halo + ((size_t)((seg - 1) * 4 + 3) * 2 + bj) * DFF + j0), m1);
;                 unpack8(*(const u32x4*)(halo + ((size_t)((seg - 1) * 4 + 2) * 2 + bj) * DFF + j0), m2); }
; #pragma unroll
;             for (int e = 0; e < 8; ++e) o[bj][e] = fb[col + e] + fw[2 * NUP + col + e] * cur[e] + fw[NUP + col + e] * m1[e] + fw[col + e] * m2[e];
;         }
;         float r8[8];
; #pragma unroll
;         for (int e = 0; e < 8; ++e) r8[e] = siluf_(o[0][e]) * o[1][e];
;         *(u32x4*)(act + t * DFF + j0) = pack8(r8);
;     }
.LBB0_819:
	s_or_b64 exec, exec, s[0:1]
	v_add_co_u32_e32 v68, vcc, s41, v78
	v_readlane_b32 s48, v253, 18
	s_nop 0
	v_addc_co_u32_e32 v69, vcc, 0, v79, vcc
	global_load_dwordx4 v[92:95], v[68:69], off offset:3072
	v_add_co_u32_e32 v68, vcc, s42, v78
	v_add_u32_e32 v0, 0xb00, v64
	s_nop 0
	v_addc_co_u32_e32 v69, vcc, 0, v79, vcc
	global_load_dwordx4 v[96:99], v[68:69], off offset:1024
	v_lshl_add_u64 v[68:69], v[78:79], 0, s[24:25]
	v_readlane_b32 s49, v253, 19
	v_readlane_b32 s60, v253, 30
	v_readlane_b32 s61, v253, 31
	global_load_dwordx4 v[100:103], v[68:69], off offset:16
	v_lshlrev_b64 v[68:69], 2, v[0:1]
	s_mov_b64 s[48:49], s[60:61]
	v_lshl_add_u64 v[112:113], s[48:49], 0, v[68:69]
	global_load_dwordx4 v[104:107], v[112:113], off
	v_lshl_add_u64 v[78:79], v[78:79], 0, s[26:27]
	global_load_dwordx4 v[108:111], v[78:79], off offset:16
	s_nop 0
	global_load_dwordx4 v[112:115], v[112:113], off offset:16
	v_readlane_b32 s58, v253, 28
	v_readlane_b32 s59, v253, 29
	s_mov_b64 s[46:47], s[58:59]
	v_lshl_add_u64 v[68:69], s[46:47], 0, v[68:69]
	s_waitcnt vmcnt(15)
	v_lshlrev_b32_e32 v0, 16, v32
	v_and_b32_e32 v2, 0xffff0000, v32
	v_lshlrev_b32_e32 v4, 16, v33
	v_and_b32_e32 v6, 0xffff0000, v33
	v_lshlrev_b32_e32 v66, 16, v34
	v_and_b32_e32 v70, 0xffff0000, v34
	v_lshlrev_b32_e32 v123, 16, v35
	v_and_b32_e32 v125, 0xffff0000, v35
	global_load_dwordx4 v[32:35], v[68:69], off offset:16
	global_load_dwordx4 v[116:119], v[68:69], off
	s_waitcnt vmcnt(14)
	v_fma_f32 v76, v52, v0, v28
	v_fma_f32 v74, v53, v2, v29
	v_fma_f32 v72, v54, v4, v30
	v_fmac_f32_e32 v31, v55, v6
	s_waitcnt vmcnt(8)
	v_lshlrev_b32_e32 v78, 16, v60
	v_lshlrev_b32_e32 v120, 16, v61
	v_mov_b32_e32 v79, v16
	v_mov_b32_e32 v121, v18
	v_fmac_f32_e32 v76, v8, v56
	v_fmac_f32_e32 v74, v9, v57
	v_fmac_f32_e32 v72, v10, v58
	v_fmac_f32_e32 v31, v11, v59
	v_fma_f32 v66, v44, v66, v24
	v_fma_f32 v6, v45, v70, v25
	v_lshlrev_b32_e32 v122, 16, v62
	v_fma_f32 v4, v46, v123, v26
	v_fmac_f32_e32 v66, v12, v48
	v_fmac_f32_e32 v6, v13, v49
	v_mov_b32_e32 v123, v20
	v_and_b32_e32 v62, 0xffff0000, v62
	v_lshlrev_b32_e32 v124, 16, v63
	v_and_b32_e32 v126, 0xffff0000, v63
	v_mov_b32_e32 v63, v21
	v_fmac_f32_e32 v27, v47, v125
	v_mov_b32_e32 v125, v22
	v_and_b32_e32 v60, 0xffff0000, v60
	v_and_b32_e32 v68, 0xffff0000, v61
	v_mov_b32_e32 v61, v17
	v_fmac_f32_e32 v4, v14, v50
	v_fmac_f32_e32 v27, v15, v51
	v_fmac_f32_e32 v76, v84, v40
	v_mov_b32_e32 v127, v23
	v_mov_b32_e32 v69, v19
	v_fmac_f32_e32 v74, v85, v41
	v_fmac_f32_e32 v72, v86, v42
	v_fmac_f32_e32 v31, v87, v43
	v_fmac_f32_e32 v66, v88, v36
	v_mov_b32_e32 v70, v31
	v_fmac_f32_e32 v6, v89, v37
	v_fmac_f32_e32 v4, v90, v38
	v_fmac_f32_e32 v27, v91, v39
	v_add_u32_e32 v80, s33, v80
	v_cmp_lt_i32_e32 vcc, s44, v80
	s_or_b64 s[10:11], vcc, s[10:11]
	v_add_u32_e32 v81, s38, v81
	v_readlane_b32 s50, v253, 20
	v_readlane_b32 s51, v253, 21
	v_readlane_b32 s52, v253, 22
	v_readlane_b32 s53, v253, 23
	s_waitcnt vmcnt(7)
	v_mov_b32_e32 v8, v92
	v_mov_b32_e32 v10, v94
	v_readlane_b32 s54, v253, 24
	v_readlane_b32 s55, v253, 25
	v_readlane_b32 s56, v253, 26
	v_readlane_b32 s57, v253, 27
	s_waitcnt vmcnt(6)
	v_mov_b32_e32 v9, v96
	v_mov_b32_e32 v11, v98
	v_pk_mul_f32 v[8:9], v[8:9], v[78:79]
	v_pk_mul_f32 v[10:11], v[10:11], v[120:121]
	v_mov_b32_e32 v96, v93
	s_waitcnt vmcnt(5)
	v_mov_b32_e32 v12, v100
	v_pk_mul_f32 v[14:15], v[96:97], v[60:61]
	v_mov_b32_e32 v98, v95
	v_pk_mul_f32 v[16:17], v[98:99], v[68:69]
	s_waitcnt vmcnt(4)
	v_add_f32_e32 v0, v104, v8
	v_add_f32_e32 v8, v106, v10
	s_waitcnt vmcnt(3)
	v_mov_b32_e32 v13, v108
	v_add_f32_e32 v0, v0, v9
	v_add_f32_e32 v11, v8, v11
	v_pk_mul_f32 v[8:9], v[12:13], v[122:123]
	v_mov_b32_e32 v108, v101
	s_waitcnt vmcnt(2)
	v_add_f32_e32 v8, v112, v8
	v_add_f32_e32 v12, v8, v9
	v_pk_mul_f32 v[8:9], v[108:109], v[62:63]
	v_add_f32_e32 v2, v105, v14
	v_add_f32_e32 v8, v113, v8
	v_add_f32_e32 v13, v8, v9
	v_mov_b32_e32 v8, v102
	v_mov_b32_e32 v9, v110
	v_pk_mul_f32 v[8:9], v[8:9], v[124:125]
	v_add_f32_e32 v2, v2, v15
	v_add_f32_e32 v8, v114, v8
	v_add_f32_e32 v14, v8, v9
	v_mul_f32_e32 v8, 0xbfb8aa3b, v76
	v_exp_f32_e32 v15, v8
	v_mov_b32_e32 v110, v103
	v_pk_mul_f32 v[8:9], v[110:111], v[126:127]
	v_add_f32_e32 v10, v107, v16
	v_add_f32_e32 v8, v115, v8
	v_add_f32_e32 v16, v8, v9
	v_add_f32_e32 v8, 1.0, v15
	v_rcp_f32_e32 v8, v8
	v_mul_f32_e32 v9, 0xbfb8aa3b, v74
	v_exp_f32_e32 v15, v9
	s_waitcnt vmcnt(0)
	v_mov_b32_e32 v9, v116
	v_pk_mul_f32 v[8:9], v[76:77], v[8:9]
	v_add_f32_e32 v10, v10, v17
	v_add_f32_e32 v0, v0, v9
	v_add_f32_e32 v9, 1.0, v15
	v_rcp_f32_e32 v116, v9
	v_mul_f32_e32 v0, v8, v0
	v_mul_f32_e32 v8, 0xbfb8aa3b, v72
	v_exp_f32_e32 v15, v8
	v_pk_mul_f32 v[8:9], v[74:75], v[116:117]
	v_readlane_b32 s62, v253, 32
	v_add_f32_e32 v2, v2, v9
	v_mul_f32_e32 v17, v8, v2
	v_add_f32_e32 v2, 1.0, v15
	v_rcp_f32_e32 v8, v2
	v_mul_f32_e32 v2, 0xbfb8aa3b, v31
	v_exp_f32_e32 v2, v2
	v_mov_b32_e32 v9, v118
	v_pk_mul_f32 v[8:9], v[72:73], v[8:9]
	v_readlane_b32 s63, v253, 33
	v_add_f32_e32 v2, 1.0, v2
	v_rcp_f32_e32 v118, v2
	v_mul_f32_e32 v2, 0xbfb8aa3b, v66
	v_exp_f32_e32 v2, v2
	v_add_f32_e32 v9, v11, v9
	v_mul_f32_e32 v11, v8, v9
	v_pk_mul_f32 v[8:9], v[70:71], v[118:119]
	v_add_f32_e32 v2, 1.0, v2
	v_add_f32_e32 v9, v10, v9
	v_mul_f32_e32 v10, v8, v9
	v_rcp_f32_e32 v8, v2
	v_mul_f32_e32 v2, 0xbfb8aa3b, v6
	v_exp_f32_e32 v2, v2
	v_mov_b32_e32 v9, v32
	v_pk_mul_f32 v[8:9], v[66:67], v[8:9]
	v_add_f32_e32 v2, 1.0, v2
	v_rcp_f32_e32 v32, v2
	v_mul_f32_e32 v2, 0xbfb8aa3b, v4
	v_exp_f32_e32 v2, v2
	v_add_f32_e32 v9, v12, v9
	v_mul_f32_e32 v12, v8, v9
	v_mov_b32_e32 v9, v34
	v_add_f32_e32 v2, 1.0, v2
	v_rcp_f32_e32 v8, v2
	v_mul_f32_e32 v2, 0xbfb8aa3b, v27
	v_exp_f32_e32 v2, v2
	v_pk_mul_f32 v[6:7], v[6:7], v[32:33]
	v_pk_mul_f32 v[4:5], v[4:5], v[8:9]
	v_add_f32_e32 v7, v13, v7
	v_add_f32_e32 v2, 1.0, v2
	v_rcp_f32_e32 v34, v2
	v_add_f32_e32 v2, v14, v5
	v_mul_f32_e32 v5, v4, v2
	v_mov_b32_e32 v2, v27
	v_pk_mul_f32 v[2:3], v[2:3], v[34:35]
	v_mul_f32_e32 v6, v6, v7
	v_add_f32_e32 v3, v16, v3
	v_mul_f32_e32 v7, v2, v3
	v_lshl_or_b32 v8, v83, 6, v82
	v_cvt_pk_bf16_f32 v2, v0, v17
	v_cvt_pk_bf16_f32 v3, v11, v10
	v_cvt_pk_bf16_f32 v4, v12, v6
	v_cvt_pk_bf16_f32 v5, v5, v7
	v_mov_b64_e32 v[6:7], s[22:23]
	v_mad_i64_i32 v[6:7], s[0:1], v8, s43, v[6:7]
	v_lshl_add_u64 v[6:7], v[64:65], 1, v[6:7]
	global_store_dwordx4 v[6:7], v[2:5], off
	s_andn2_b64 exec, exec, s[10:11]
	s_cbranch_execz .LBB0_836
	s_nop 0
	s_nop 0
	s_nop 0
	s_nop 0
	s_nop 0
	s_nop 0

; #define PG8_BAR __builtin_amdgcn_s_barrier()
; template <class Epi, class Sched, bool ALIGN_EPI = false, bool SP2 = false>
; __device__ __forceinline__ void gemm_phase(PG8_LAS unsigned char* lds, const Gemm g, const Sched& S, const Epi& E) {
;     ...
;         if (!has_next) break;
; #pragma unroll
;         for (int a = 0; a < 2; ++a)
; #pragma unroll
;             for (int b = 0; b < 2; ++b)
; #pragma unroll
;                 for (int m = 0; m < 4; ++m)
; #pragma unroll
;                     for (int n = 0; n < 2; ++n) acc[a][b][m][n] = (f32x4){0.f, 0.f, 0.f, 0.f};
;         cur = nxt; cA = nA; cB = nB; ++ui;
;         if constexpr (ALIGN_EPI) { if (wr == 1) PG8_BAR; }
.LBB0_901:
	s_andn2_b64 vcc, exec, s[6:7]
	s_mov_b32 s8, s49
	s_mov_b32 s51, s50
	s_mov_b64 s[30:31], s[26:27]
	s_mov_b64 s[28:29], s[4:5]
	s_cbranch_vccz .LBB0_935
	s_nop 0
	s_nop 0
	s_nop 0
	s_nop 0
	s_nop 0
	s_nop 0
	s_nop 0
	s_nop 0
	s_nop 0
	s_nop 0
	s_nop 0

; __device__ __forceinline__ void phase_final(const Args& a) {
;     const int tid = threadIdx.x, lane = tid & 63, wave = tid >> 6; const float* fw = a.in[16];
;     const bf16_t* yb = (const bf16_t*)(a.ws + WS_YB); const float* ss3 = (const float*)(a.ws + WS_SS3);
;     f32x4 nwv[4];
; #pragma unroll
;     for (int j = 0; j < 2; ++j) { nwv[2 * j] = *(const f32x4*)(fw + 512 * j + 8 * lane); nwv[2 * j + 1] = *(const f32x4*)(fw + 512 * j + 8 * lane + 4); }
;     for (int row = blockIdx.x * 8 + wave; row < M; row += gridDim.x * 8) {
.LBB0_988:
	s_or_b64 exec, exec, s[0:1]
	v_readlane_b32 s0, v253, 17
	s_bitcmp0_b32 s0, 10
	s_waitcnt lgkmcnt(0)
	s_barrier
	s_cbranch_scc1 .LBB0_992
	s_waitcnt vmcnt(4)
	v_lshl_add_u32 v16, s82, 3, v153
	s_mov_b32 s0, 0x8000
	v_cmp_gt_i32_e32 vcc, s0, v16
	s_and_saveexec_b64 s[0:1], vcc
	s_cbranch_execz .LBB0_992
	v_lshlrev_b32_e32 v0, 3, v152
	v_and_b32_e32 v17, 0x1f8, v0
	s_waitcnt vmcnt(3)
	v_lshlrev_b32_e32 v20, 2, v17
	global_load_dwordx4 v[0:3], v20, s[76:77] offset:16
	global_load_dwordx4 v[4:7], v20, s[76:77]
	global_load_dwordx4 v[8:11], v20, s[76:77] offset:2064
	global_load_dwordx4 v[12:15], v20, s[76:77] offset:2048
	s_waitcnt vmcnt(6)
	v_mov_b32_e32 v21, 0
	v_lshl_add_u64 v[18:19], s[78:79], 0, v[20:21]
	v_lshlrev_b32_e32 v20, 1, v17
	v_lshl_add_u64 v[20:21], s[16:17], 0, v[20:21]
	s_mov_b64 s[0:1], 0xc000000
	s_lshl_b32 s2, s80, 3
	v_lshl_add_u64 v[20:21], v[20:21], 0, s[0:1]
	s_mov_b64 s[0:1], 0
	v_mov_b32_e32 v22, 0x358637bd
	s_mov_b32 s3, 0x800000
	s_movk_i32 s4, 0x7fff
	s_nop 0
	s_nop 0
	s_nop 0
	s_nop 0
	s_nop 0
